# code placement: one s_nop 0 before the proj, outproj and ffnup1 glds tile loops so every hand-written k-loop head sits at 4 mod 8 bytes
# baseline (speedup 1.0000x reference)
.LBB0_189:
	s_cmp_lt_i32 s88, 3
	s_cselect_b64 s[18:19], -1, 0
	s_and_b64 s[4:5], s[18:19], s[4:5]
	s_andn2_b64 vcc, exec, s[4:5]
	s_cbranch_vccnz .LBB0_426
	s_add_u32 s16, s34, 0x28c4000
	s_addc_u32 s17, s35, 0
	s_add_u32 s6, s34, 0x8a44000
	s_addc_u32 s7, s35, 0
	s_add_u32 s8, s0, 0x120
	s_addc_u32 s9, s1, 0
	s_cmpk_lt_i32 s2, 0x100
	s_cbranch_scc0 .LBB0_197
	s_load_dword s9, s[0:1], 0x120
	v_readfirstlane_b32 s42, v205
	v_and_b32_e32 v192, 15, v204
	v_bfe_u32 v193, v204, 4, 2
	v_lshrrev_b32_e32 v194, 8, v204
	v_bfe_u32 v195, v204, 6, 2
	v_bfe_u32 v196, v204, 1, 3
	v_xor_b32_e32 v197, v193, v196
	v_xor_b32_e32 v198, 4, v197
	v_lshlrev_b32_e32 v197, 4, v197
	v_lshlrev_b32_e32 v198, 4, v198
	v_lshlrev_b32_e32 v199, 14, v194
	v_lshl_add_u32 v199, v192, 7, v199
	v_add_u32_e32 v242, v199, v197
	v_add_u32_e32 v243, v199, v198
	v_lshlrev_b32_e32 v199, 13, v195
	v_lshl_add_u32 v199, v192, 7, v199
	v_add_u32_e32 v199, 0x8000, v199
	v_add_u32_e32 v244, v199, v197
	v_add_u32_e32 v245, v199, v198
	v_add_u32_e32 v246, 0x10000, v242
	v_add_u32_e32 v248, 0x10000, v244
	v_add_u32_e32 v247, 0x10000, v243
	v_add_u32_e32 v249, 0x10000, v245
	v_lshrrev_b32_e32 v199, 3, v204
	v_and_b32_e32 v200, 7, v204
	v_bfe_u32 v201, v204, 4, 3
	v_xor_b32_e32 v200, v200, v201
	v_lshlrev_b32_e32 v200, 4, v200
	v_lshl_add_u32 v238, v199, 11, v200
	v_add_u32_e32 v239, 0x20000, v238
	v_add_u32_e32 v240, 0x40000, v238
	v_add_u32_e32 v241, 0x60000, v238
	s_lshl_b32 s42, s42, 10
	s_mov_b32 s8, s2
	s_and_b32 s44, s8, 7
	s_lshl_b32 s44, s44, 5
	s_lshr_b32 s45, s8, 3
	s_add_i32 s44, s44, s45
	s_lshr_b32 s45, s44, 6
	s_and_b32 s44, s44, 63
	s_and_b32 s98, s44, 7
	s_lshl_b32 s45, s45, 3
	s_add_i32 s45, s45, s98
	s_lshl_b32 s14, s45, 8
	s_lshr_b32 s44, s44, 3
	s_lshl_b32 s15, s44, 8
	s_mul_i32 s44, s14, 0x800
	s_add_u32 s44, s44, 0x8a44000
	s_add_u32 s10, s34, s44
	s_addc_u32 s11, s35, 0
	s_mul_i32 s44, s15, 0x800
	s_add_u32 s44, s44, 0x0
	s_add_u32 s12, s34, s44
	s_addc_u32 s13, s35, 0
	s_waitcnt vmcnt(0) lgkmcnt(0)
	s_barrier
	s_add_u32 m0, s42, 0x0
	s_nop 0
	global_load_lds_dwordx4 v238, s[10:11]
	s_add_u32 m0, s42, 0x2000
	s_nop 0
	global_load_lds_dwordx4 v239, s[10:11]
	s_add_u32 m0, s42, 0x4000
	s_nop 0
	global_load_lds_dwordx4 v240, s[10:11]
	s_add_u32 m0, s42, 0x6000
	s_nop 0
	global_load_lds_dwordx4 v241, s[10:11]
	s_add_u32 m0, s42, 0x8000
	s_nop 0
	global_load_lds_dwordx4 v238, s[12:13]
	s_add_u32 m0, s42, 0xa000
	s_nop 0
	global_load_lds_dwordx4 v239, s[12:13]
	s_add_u32 m0, s42, 0xc000
	s_nop 0
	global_load_lds_dwordx4 v240, s[12:13]
	s_add_u32 m0, s42, 0xe000
	s_nop 0
	global_load_lds_dwordx4 v241, s[12:13]
	s_waitcnt vmcnt(0)
	s_nop 0

.LBB0_1014:
	s_cmp_lt_i32 s88, 8
	s_cselect_b64 s[4:5], -1, 0
	s_and_b64 s[6:7], s[4:5], s[6:7]
	s_andn2_b64 vcc, exec, s[6:7]
	s_cbranch_vccnz .LBB0_1023
	s_cmpk_gt_i32 s2, 0xff
	s_cbranch_scc1 .LBB0_1023
	s_load_dword s9, s[0:1], 0x120
	v_readfirstlane_b32 s42, v205
	v_and_b32_e32 v192, 15, v204
	v_bfe_u32 v193, v204, 4, 2
	v_lshrrev_b32_e32 v194, 8, v204
	v_bfe_u32 v195, v204, 6, 2
	v_bfe_u32 v196, v204, 1, 3
	v_xor_b32_e32 v197, v193, v196
	v_xor_b32_e32 v198, 4, v197
	v_lshlrev_b32_e32 v197, 4, v197
	v_lshlrev_b32_e32 v198, 4, v198
	v_lshlrev_b32_e32 v199, 14, v194
	v_lshl_add_u32 v199, v192, 7, v199
	v_add_u32_e32 v242, v199, v197
	v_add_u32_e32 v243, v199, v198
	v_lshlrev_b32_e32 v199, 13, v195
	v_lshl_add_u32 v199, v192, 7, v199
	v_add_u32_e32 v199, 0x8000, v199
	v_add_u32_e32 v244, v199, v197
	v_add_u32_e32 v245, v199, v198
	v_add_u32_e32 v246, 0x10000, v242
	v_add_u32_e32 v248, 0x10000, v244
	v_add_u32_e32 v247, 0x10000, v243
	v_add_u32_e32 v249, 0x10000, v245
	v_lshrrev_b32_e32 v199, 3, v204
	v_and_b32_e32 v200, 7, v204
	v_bfe_u32 v201, v204, 4, 3
	v_xor_b32_e32 v200, v200, v201
	v_lshlrev_b32_e32 v200, 4, v200
	v_lshl_add_u32 v238, v199, 11, v200
	v_add_u32_e32 v239, 0x20000, v238
	v_add_u32_e32 v240, 0x40000, v238
	v_add_u32_e32 v241, 0x60000, v238
	s_lshl_b32 s42, s42, 10
	s_mov_b32 s8, s2
	s_and_b32 s44, s8, 7
	s_lshl_b32 s44, s44, 5
	s_lshr_b32 s45, s8, 3
	s_add_i32 s44, s44, s45
	s_lshr_b32 s45, s44, 7
	s_and_b32 s44, s44, 127
	s_and_b32 s98, s44, 3
	s_lshl_b32 s15, s98, 8
	s_lshr_b32 s44, s44, 2
	s_lshl_b32 s14, s44, 8
	s_mul_i32 s44, s14, 0x800
	s_mul_i32 s98, s45, 0x400
	s_add_u32 s44, s44, s98
	s_add_u32 s44, s44, 0x9a44000
	s_add_u32 s10, s34, s44
	s_addc_u32 s11, s35, 0
	s_mul_i32 s44, s15, 0x800
	s_add_u32 s44, s44, s98
	s_add_u32 s44, s44, 0x520000
	s_add_u32 s12, s34, s44
	s_addc_u32 s13, s35, 0
	s_lshl_b32 s45, s45, 16
	s_or_b32 s14, s14, s45
	s_waitcnt vmcnt(0) lgkmcnt(0)
	s_barrier
	s_add_u32 m0, s42, 0x0
	s_nop 0
	global_load_lds_dwordx4 v238, s[10:11]
	s_add_u32 m0, s42, 0x2000
	s_nop 0
	global_load_lds_dwordx4 v239, s[10:11]
	s_add_u32 m0, s42, 0x4000
	s_nop 0
	global_load_lds_dwordx4 v240, s[10:11]
	s_add_u32 m0, s42, 0x6000
	s_nop 0
	global_load_lds_dwordx4 v241, s[10:11]
	s_add_u32 m0, s42, 0x8000
	s_nop 0
	global_load_lds_dwordx4 v238, s[12:13]
	s_add_u32 m0, s42, 0xa000
	s_nop 0
	global_load_lds_dwordx4 v239, s[12:13]
	s_add_u32 m0, s42, 0xc000
	s_nop 0
	global_load_lds_dwordx4 v240, s[12:13]
	s_add_u32 m0, s42, 0xe000
	s_nop 0
	global_load_lds_dwordx4 v241, s[12:13]
	s_waitcnt vmcnt(0)
	s_nop 0

.LBB0_1443:
	s_cmp_lt_i32 s88, 16
	s_cselect_b64 s[6:7], -1, 0
	s_and_b64 s[4:5], s[6:7], s[4:5]
	s_andn2_b64 vcc, exec, s[4:5]
	s_cbranch_vccnz .LBB0_1451
	s_cmpk_gt_i32 s2, 0x2bf
	s_cbranch_scc1 .LBB0_1451
	s_load_dword s9, s[0:1], 0x120
	v_readfirstlane_b32 s42, v205
	v_and_b32_e32 v192, 15, v204
	v_bfe_u32 v193, v204, 4, 2
	v_lshrrev_b32_e32 v194, 8, v204
	v_bfe_u32 v195, v204, 6, 2
	v_bfe_u32 v196, v204, 1, 3
	v_xor_b32_e32 v197, v193, v196
	v_xor_b32_e32 v198, 4, v197
	v_lshlrev_b32_e32 v197, 4, v197
	v_lshlrev_b32_e32 v198, 4, v198
	v_lshlrev_b32_e32 v199, 14, v194
	v_lshl_add_u32 v199, v192, 7, v199
	v_add_u32_e32 v242, v199, v197
	v_add_u32_e32 v243, v199, v198
	v_lshlrev_b32_e32 v199, 13, v195
	v_lshl_add_u32 v199, v192, 7, v199
	v_add_u32_e32 v199, 0x8000, v199
	v_add_u32_e32 v244, v199, v197
	v_add_u32_e32 v245, v199, v198
	v_add_u32_e32 v246, 0x10000, v242
	v_add_u32_e32 v248, 0x10000, v244
	v_add_u32_e32 v247, 0x10000, v243
	v_add_u32_e32 v249, 0x10000, v245
	v_lshrrev_b32_e32 v199, 3, v204
	v_and_b32_e32 v200, 7, v204
	v_bfe_u32 v201, v204, 4, 3
	v_xor_b32_e32 v200, v200, v201
	v_lshlrev_b32_e32 v200, 4, v200
	v_lshl_add_u32 v238, v199, 11, v200
	v_add_u32_e32 v239, 0x20000, v238
	v_add_u32_e32 v240, 0x40000, v238
	v_add_u32_e32 v241, 0x60000, v238
	s_lshl_b32 s42, s42, 10
	s_mov_b32 s8, s2
	s_and_b32 s44, s8, 7
	s_mulk_i32 s44, 0x58
	s_lshr_b32 s45, s8, 3
	s_add_i32 s44, s44, s45
	s_cmpk_ge_i32 s44, 176
	s_cselect_b32 s45, 1, 0
	s_cmpk_ge_i32 s44, 352
	s_cselect_b32 s98, 1, 0
	s_add_i32 s45, s45, s98
	s_cmpk_ge_i32 s44, 528
	s_cselect_b32 s98, 1, 0
	s_add_i32 s45, s45, s98
	s_mul_i32 s98, s45, 176
	s_sub_i32 s44, s44, s98
	s_and_b32 s98, s44, 7
	s_lshl_b32 s45, s45, 3
	s_add_i32 s45, s45, s98
	s_lshl_b32 s14, s45, 8
	s_lshr_b32 s44, s44, 3
	s_lshl_b32 s15, s44, 8
	s_mul_i32 s44, s14, 0x800
	s_add_u32 s44, s44, 0x8a44000
	s_add_u32 s10, s34, s44
	s_addc_u32 s11, s35, 0
	s_mul_i32 s44, s15, 0x800
	s_add_u32 s44, s44, 0x12a0000
	s_add_u32 s12, s34, s44
	s_addc_u32 s13, s35, 0
	s_waitcnt vmcnt(0) lgkmcnt(0)
	s_barrier
	s_add_u32 m0, s42, 0x0
	s_nop 0
	global_load_lds_dwordx4 v238, s[10:11]
	s_add_u32 m0, s42, 0x2000
	s_nop 0
	global_load_lds_dwordx4 v239, s[10:11]
	s_add_u32 m0, s42, 0x4000
	s_nop 0
	global_load_lds_dwordx4 v240, s[10:11]
	s_add_u32 m0, s42, 0x6000
	s_nop 0
	global_load_lds_dwordx4 v241, s[10:11]
	s_add_u32 m0, s42, 0x8000
	s_nop 0
	global_load_lds_dwordx4 v238, s[12:13]
	s_add_u32 m0, s42, 0xa000
	s_nop 0
	global_load_lds_dwordx4 v239, s[12:13]
	s_add_u32 m0, s42, 0xc000
	s_nop 0
	global_load_lds_dwordx4 v240, s[12:13]
	s_add_u32 m0, s42, 0xe000
	s_nop 0
	global_load_lds_dwordx4 v241, s[12:13]
	s_waitcnt vmcnt(0)
	s_nop 0
